# bundle: scalar O-rescale in attention, up-proj epilogue column constants cached in dead registers, conv-state warm-up loads for sample tiles
# speedup vs baseline: 1.0078x; 1.0054x over previous
.LBB0_1393:
	v_lshl_or_b32 v160, s73, 6, v169
	v_mov_b32_e32 v203, v167
	v_lshl_add_u32 v132, v160, 3, s67
	ds_read_b64 v[132:133], v132
	v_cmp_gt_u32_e64 s[46:47], 2, v169
	s_waitcnt lgkmcnt(0)
	v_pk_mul_f32 v[152:153], v[132:133], s[96:97] op_sel_hi:[1,0]
	v_fma_f32 v132, -v152, v152, v153
	v_max_f32_e32 v132, 0, v132
	v_add_f32_e32 v132, 0x3727c5ac, v132
	v_rsq_f32_e32 v180, v132
	ds_read_b128 v[222:225], v203 offset:2048
	ds_read_b128 v[226:229], v203 offset:2560
	ds_read_b128 v[230:233], v203 offset:2064
	ds_read_b128 v[234:237], v203 offset:2576
	v_mul_f32_e64 v188, v180, -v152
	ds_read_b128 v[238:241], v203 offset:3072
	ds_read_b128 v[244:247], v203 offset:3584
	s_waitcnt lgkmcnt(0)
	v_pk_fma_f32 v[132:133], v[222:223], v[188:189], v[226:227] op_sel_hi:[1,0,1]
	v_pk_fma_f32 v[134:135], v[224:225], v[188:189], v[228:229] op_sel_hi:[1,0,1]
	v_pk_fma_f32 v[136:137], v[230:231], v[188:189], v[234:235] op_sel_hi:[1,0,1]
	v_pk_fma_f32 v[138:139], v[232:233], v[188:189], v[236:237] op_sel_hi:[1,0,1]
	ds_read_b128 v[144:147], v203 offset:3088
	ds_read_b128 v[184:187], v203 offset:3600
	v_pk_fma_f32 v[132:133], v[124:125], v[180:181], v[132:133] op_sel_hi:[1,0,1]
	v_pk_fma_f32 v[134:135], v[126:127], v[180:181], v[134:135] op_sel_hi:[1,0,1]
	v_pk_fma_f32 v[136:137], v[120:121], v[180:181], v[136:137] op_sel_hi:[1,0,1]
	v_pk_fma_f32 v[138:139], v[122:123], v[180:181], v[138:139] op_sel_hi:[1,0,1]
	v_pk_fma_f32 v[148:149], v[238:239], v[188:189], v[244:245] op_sel_hi:[1,0,1]
	v_pk_fma_f32 v[150:151], v[240:241], v[188:189], v[246:247] op_sel_hi:[1,0,1]
	s_waitcnt lgkmcnt(0)
	v_pk_fma_f32 v[144:145], v[144:145], v[188:189], v[184:185] op_sel_hi:[1,0,1]
	v_pk_fma_f32 v[146:147], v[146:147], v[188:189], v[186:187] op_sel_hi:[1,0,1]
	s_and_b64 s[4:5], s[4:5], s[46:47]
	v_cmp_eq_u32_e64 s[42:43], 0, v169
	v_cmp_lt_u32_e32 vcc, 1, v169
	v_cmp_eq_u32_e64 s[44:45], 1, v169
	v_ashrrev_i32_e32 v175, 31, v174
	v_pk_fma_f32 v[150:151], v[94:95], v[180:181], v[150:151] op_sel_hi:[1,0,1]
	v_pk_fma_f32 v[144:145], v[88:89], v[180:181], v[144:145] op_sel_hi:[1,0,1]
	v_pk_fma_f32 v[146:147], v[90:91], v[180:181], v[146:147] op_sel_hi:[1,0,1]
	v_mov_b32_dpp v173, v132 row_ror:1 row_mask:0xf bank_mask:0xf
	v_mov_b32_dpp v185, v133 row_ror:1 row_mask:0xf bank_mask:0xf
	v_mov_b32_dpp v184, v132 row_ror:2 row_mask:0xf bank_mask:0xf
	v_mov_b32_dpp v186, v133 row_ror:2 row_mask:0xf bank_mask:0xf
	v_mov_b32_dpp v187, v134 row_ror:1 row_mask:0xf bank_mask:0xf
	v_mov_b32_dpp v194, v135 row_ror:1 row_mask:0xf bank_mask:0xf
	v_mov_b32_dpp v188, v134 row_ror:2 row_mask:0xf bank_mask:0xf
	v_mov_b32_dpp v189, v135 row_ror:2 row_mask:0xf bank_mask:0xf
	v_mov_b32_dpp v195, v136 row_ror:1 row_mask:0xf bank_mask:0xf
	v_mov_b32_dpp v197, v137 row_ror:1 row_mask:0xf bank_mask:0xf
	v_mov_b32_dpp v196, v136 row_ror:2 row_mask:0xf bank_mask:0xf
	v_mov_b32_dpp v198, v137 row_ror:2 row_mask:0xf bank_mask:0xf
	v_mov_b32_dpp v201, v138 row_ror:1 row_mask:0xf bank_mask:0xf
	v_mov_b32_dpp v202, v139 row_ror:1 row_mask:0xf bank_mask:0xf
	v_mov_b32_dpp v199, v138 row_ror:2 row_mask:0xf bank_mask:0xf
	v_mov_b32_dpp v200, v139 row_ror:2 row_mask:0xf bank_mask:0xf
	v_pk_fma_f32 v[148:149], v[92:93], v[180:181], v[148:149] op_sel_hi:[1,0,1]
	s_xor_b64 s[8:9], s[4:5], -1
	s_and_saveexec_b64 s[4:5], s[8:9]
	s_cbranch_execz .LBB0_1395
	ds_read_b128 v[178:181], v203 offset:1040
	ds_read_b128 v[204:207], v203 offset:528
	ds_read_b128 v[152:155], v203
	ds_read_b128 v[208:211], v203 offset:16
	ds_read_b128 v[212:215], v203 offset:1552
	v_cndmask_b32_e64 v158, v158, v164, s[44:45]
	v_cndmask_b32_e64 v159, v159, v165, s[44:45]
	v_cndmask_b32_e32 v159, v159, v200, vcc
	v_cndmask_b32_e32 v158, v158, v199, vcc
	v_cndmask_b32_e64 v177, v202, v165, s[42:43]
	v_cndmask_b32_e64 v176, v201, v164, s[42:43]
	s_waitcnt lgkmcnt(0)
	v_pk_fma_f32 v[158:159], v[158:159], v[210:211], v[214:215]
	v_cndmask_b32_e64 v156, v156, v162, s[44:45]
	v_pk_fma_f32 v[158:159], v[176:177], v[206:207], v[158:159]
	v_cndmask_b32_e64 v157, v157, v163, s[44:45]
	v_pk_fma_f32 v[158:159], v[138:139], v[180:181], v[158:159]
	v_cndmask_b32_e32 v157, v157, v198, vcc
	v_pk_mul_f32 v[164:165], v[146:147], v[158:159]
	v_pk_mul_f32 v[158:159], v[158:159], s[20:21] op_sel_hi:[1,0]
	v_cndmask_b32_e32 v156, v156, v196, vcc
	v_exp_f32_e32 v158, v158
	v_exp_f32_e32 v159, v159
	v_pk_fma_f32 v[156:157], v[156:157], v[208:209], v[212:213]
	v_cndmask_b32_e64 v130, v130, v142, s[44:45]
	v_cndmask_b32_e64 v131, v131, v143, s[44:45]
	v_pk_add_f32 v[158:159], v[158:159], 1.0 op_sel_hi:[1,0]
	v_cndmask_b32_e32 v131, v131, v189, vcc
	v_rcp_f32_e32 v158, v158
	v_rcp_f32_e32 v159, v159
	v_cndmask_b32_e32 v130, v130, v188, vcc
	v_cndmask_b32_e64 v181, v194, v143, s[42:43]
	v_cndmask_b32_e64 v180, v187, v142, s[42:43]
	v_pk_mul_f32 v[176:177], v[164:165], v[158:159]
	v_cndmask_b32_e64 v159, v197, v163, s[42:43]
	v_cndmask_b32_e64 v158, v195, v162, s[42:43]
	v_pk_fma_f32 v[156:157], v[158:159], v[204:205], v[156:157]
	ds_read_b128 v[204:207], v203 offset:1536
	v_pk_fma_f32 v[156:157], v[136:137], v[178:179], v[156:157]
	ds_read_b128 v[162:165], v203 offset:512
	v_pk_mul_f32 v[158:159], v[144:145], v[156:157]
	v_pk_mul_f32 v[156:157], v[156:157], s[20:21] op_sel_hi:[1,0]
	s_waitcnt lgkmcnt(0)
	v_pk_fma_f32 v[130:131], v[130:131], v[154:155], v[206:207]
	v_exp_f32_e32 v156, v156
	v_exp_f32_e32 v157, v157
	v_pk_fma_f32 v[130:131], v[180:181], v[164:165], v[130:131]
	v_cndmask_b32_e64 v128, v128, v140, s[44:45]
	v_cndmask_b32_e64 v129, v129, v141, s[44:45]
	v_pk_add_f32 v[156:157], v[156:157], 1.0 op_sel_hi:[1,0]
	v_cndmask_b32_e32 v129, v129, v186, vcc
	v_rcp_f32_e32 v156, v156
	v_rcp_f32_e32 v157, v157
	v_cndmask_b32_e32 v128, v128, v184, vcc
	v_pk_fma_f32 v[128:129], v[128:129], v[152:153], v[204:205]
	s_movk_i32 s8, 0x1600
	v_pk_mul_f32 v[178:179], v[158:159], v[156:157]
	ds_read_b128 v[156:159], v203 offset:1024
	s_waitcnt lgkmcnt(0)
	v_pk_fma_f32 v[130:131], v[134:135], v[158:159], v[130:131]
	s_nop 0
	v_pk_mul_f32 v[142:143], v[150:151], v[130:131]
	v_pk_mul_f32 v[130:131], v[130:131], s[20:21] op_sel_hi:[1,0]
	s_nop 0
	v_exp_f32_e32 v130, v130
	v_exp_f32_e32 v131, v131
	s_nop 0
	v_pk_add_f32 v[130:131], v[130:131], 1.0 op_sel_hi:[1,0]
	s_nop 0
	v_rcp_f32_e32 v130, v130
	v_rcp_f32_e32 v131, v131
	s_nop 0
	v_pk_mul_f32 v[130:131], v[142:143], v[130:131]
	v_cndmask_b32_e64 v143, v185, v141, s[42:43]
	v_cndmask_b32_e64 v142, v173, v140, s[42:43]
	v_pk_fma_f32 v[128:129], v[142:143], v[162:163], v[128:129]
	v_lshl_add_u32 v142, s56, 8, v160
	v_pk_fma_f32 v[128:129], v[132:133], v[156:157], v[128:129]
	s_nop 0
	v_pk_mul_f32 v[140:141], v[148:149], v[128:129]
	v_pk_mul_f32 v[128:129], v[128:129], s[20:21] op_sel_hi:[1,0]
	s_nop 0
	v_exp_f32_e32 v128, v128
	v_exp_f32_e32 v129, v129
	s_nop 0
	v_pk_add_f32 v[128:129], v[128:129], 1.0 op_sel_hi:[1,0]
	s_nop 0
	v_rcp_f32_e32 v128, v128
	v_rcp_f32_e32 v129, v129
	s_nop 0
	v_pk_mul_f32 v[128:129], v[140:141], v[128:129]
	v_mov_b64_e32 v[140:141], s[60:61]
	v_mad_i64_i32 v[140:141], s[8:9], v142, s8, v[140:141]
	v_cvt_pk_bf16_f32 v128, v128, v129
	v_cvt_pk_bf16_f32 v129, v130, v131
	v_cvt_pk_bf16_f32 v130, v178, v179
	v_cvt_pk_bf16_f32 v131, v176, v177
	v_lshl_add_u64 v[140:141], v[174:175], 1, v[140:141]
	global_store_dwordx4 v[140:141], v[128:131], off

.LBB0_1397:
	s_or_b64 exec, exec, s[4:5]
	v_or_b32_e32 v208, 16, v160
	v_mov_b32_e32 v209, v167
	v_lshl_add_u32 v128, v208, 3, s67
	ds_read_b64 v[136:137], v128
	s_waitcnt lgkmcnt(0)
	v_pk_mul_f32 v[136:137], v[136:137], s[96:97] op_sel_hi:[1,0]
	v_fma_f32 v137, -v136, v136, v137
	v_max_f32_e32 v137, 0, v137
	v_add_f32_e32 v137, 0x3727c5ac, v137
	v_rsq_f32_e32 v150, v137
	s_nop 0
	v_mul_f32_e64 v152, v150, -v136
	v_pk_fma_f32 v[128:129], v[222:223], v[152:153], v[226:227] op_sel_hi:[1,0,1]
	v_pk_fma_f32 v[130:131], v[224:225], v[152:153], v[228:229] op_sel_hi:[1,0,1]
	v_pk_fma_f32 v[136:137], v[116:117], v[150:151], v[128:129] op_sel_hi:[1,0,1]
	v_pk_fma_f32 v[128:129], v[230:231], v[152:153], v[234:235] op_sel_hi:[1,0,1]
	v_pk_fma_f32 v[140:141], v[118:119], v[150:151], v[130:131] op_sel_hi:[1,0,1]
	v_pk_fma_f32 v[180:181], v[112:113], v[150:151], v[128:129] op_sel_hi:[1,0,1]
	v_pk_fma_f32 v[138:139], v[232:233], v[152:153], v[236:237] op_sel_hi:[1,0,1]
	ds_read_b128 v[88:91], v209 offset:3088
	ds_read_b128 v[92:95], v209 offset:3600
	v_pk_fma_f32 v[190:191], v[114:115], v[150:151], v[138:139] op_sel_hi:[1,0,1]
	s_waitcnt lgkmcnt(0)
	v_pk_fma_f32 v[130:131], v[240:241], v[152:153], v[246:247] op_sel_hi:[1,0,1]
	v_pk_fma_f32 v[128:129], v[238:239], v[152:153], v[244:245] op_sel_hi:[1,0,1]
	v_pk_fma_f32 v[138:139], v[86:87], v[150:151], v[130:131] op_sel_hi:[1,0,1]
	v_pk_fma_f32 v[130:131], v[88:89], v[152:153], v[92:93] op_sel_hi:[1,0,1]
	v_pk_fma_f32 v[142:143], v[84:85], v[150:151], v[128:129] op_sel_hi:[1,0,1]
	v_pk_fma_f32 v[204:205], v[80:81], v[150:151], v[130:131] op_sel_hi:[1,0,1]
	v_pk_fma_f32 v[130:131], v[90:91], v[152:153], v[94:95] op_sel_hi:[1,0,1]
	ds_read_b128 v[120:123], v209 offset:1040
	v_pk_fma_f32 v[206:207], v[82:83], v[150:151], v[130:131] op_sel_hi:[1,0,1]
	ds_read_b128 v[124:127], v209 offset:16
	ds_read_b128 v[148:151], v209 offset:1552
	ds_read_b128 v[176:179], v209 offset:528
	ds_read_b128 v[128:131], v209
	v_mov_b32_dpp v210, v190 row_ror:1 row_mask:0xf bank_mask:0xf
	v_mov_b32_dpp v211, v191 row_ror:1 row_mask:0xf bank_mask:0xf
	v_mov_b32_dpp v212, v190 row_ror:2 row_mask:0xf bank_mask:0xf
	v_mov_b32_dpp v213, v191 row_ror:2 row_mask:0xf bank_mask:0xf
	v_cndmask_b32_e64 v203, v211, v202, s[42:43]
	v_cndmask_b32_e64 v202, v210, v201, s[42:43]
	v_cndmask_b32_e32 v201, v200, v213, vcc
	v_cndmask_b32_e32 v200, v199, v212, vcc
	v_mov_b32_dpp v163, v180 row_ror:2 row_mask:0xf bank_mask:0xf
	v_mov_b32_dpp v165, v181 row_ror:2 row_mask:0xf bank_mask:0xf
	s_waitcnt lgkmcnt(0)
	v_pk_fma_f32 v[146:147], v[200:201], v[126:127], v[150:151]
	v_mov_b32_dpp v162, v180 row_ror:1 row_mask:0xf bank_mask:0xf
	v_mov_b32_dpp v164, v181 row_ror:1 row_mask:0xf bank_mask:0xf
	v_pk_fma_f32 v[146:147], v[202:203], v[178:179], v[146:147]
	v_cndmask_b32_e32 v179, v198, v165, vcc
	v_cndmask_b32_e32 v178, v196, v163, vcc
	v_cndmask_b32_e64 v151, v164, v197, s[42:43]
	v_cndmask_b32_e64 v150, v162, v195, s[42:43]
	v_pk_fma_f32 v[144:145], v[178:179], v[124:125], v[148:149]
	v_pk_fma_f32 v[134:135], v[190:191], v[122:123], v[146:147]
	v_pk_fma_f32 v[144:145], v[150:151], v[176:177], v[144:145]
	v_pk_mul_f32 v[146:147], v[134:135], s[20:21] op_sel_hi:[1,0]
	v_pk_fma_f32 v[132:133], v[180:181], v[120:121], v[144:145]
	v_exp_f32_e32 v146, v146
	v_pk_mul_f32 v[144:145], v[132:133], s[20:21] op_sel_hi:[1,0]
	v_exp_f32_e32 v147, v147
	v_exp_f32_e32 v144, v144
	v_exp_f32_e32 v145, v145
	v_pk_mul_f32 v[134:135], v[206:207], v[134:135]
	v_pk_add_f32 v[146:147], v[146:147], 1.0 op_sel_hi:[1,0]
	v_pk_mul_f32 v[132:133], v[204:205], v[132:133]
	v_pk_add_f32 v[144:145], v[144:145], 1.0 op_sel_hi:[1,0]
	v_rcp_f32_e32 v146, v146
	v_rcp_f32_e32 v147, v147
	v_rcp_f32_e32 v148, v144
	v_rcp_f32_e32 v149, v145
	v_pk_mul_f32 v[144:145], v[134:135], v[146:147]
	v_pk_mul_f32 v[146:147], v[132:133], v[148:149]
	ds_read_b128 v[132:135], v209 offset:1024
	ds_read_b128 v[148:151], v209 offset:1536
	ds_read_b128 v[176:179], v209 offset:512
	v_mov_b32_dpp v157, v140 row_ror:2 row_mask:0xf bank_mask:0xf
	v_mov_b32_dpp v158, v141 row_ror:2 row_mask:0xf bank_mask:0xf
	v_mov_b32_dpp v156, v140 row_ror:1 row_mask:0xf bank_mask:0xf
	v_mov_b32_dpp v159, v141 row_ror:1 row_mask:0xf bank_mask:0xf
	v_cndmask_b32_e32 v189, v189, v158, vcc
	v_cndmask_b32_e32 v188, v188, v157, vcc
	v_mov_b32_dpp v153, v136 row_ror:2 row_mask:0xf bank_mask:0xf
	v_mov_b32_dpp v155, v137 row_ror:2 row_mask:0xf bank_mask:0xf
	v_cndmask_b32_e64 v181, v159, v194, s[42:43]
	v_cndmask_b32_e64 v180, v156, v187, s[42:43]
	s_waitcnt lgkmcnt(0)
	v_pk_fma_f32 v[130:131], v[188:189], v[130:131], v[150:151]
	v_mov_b32_dpp v152, v136 row_ror:1 row_mask:0xf bank_mask:0xf
	v_mov_b32_dpp v154, v137 row_ror:1 row_mask:0xf bank_mask:0xf
	v_pk_fma_f32 v[130:131], v[180:181], v[178:179], v[130:131]
	v_cndmask_b32_e32 v151, v186, v155, vcc
	v_cndmask_b32_e32 v150, v184, v153, vcc
	v_pk_fma_f32 v[130:131], v[140:141], v[134:135], v[130:131]
	v_cndmask_b32_e64 v141, v154, v185, s[42:43]
	v_cndmask_b32_e64 v140, v152, v173, s[42:43]
	v_pk_fma_f32 v[128:129], v[150:151], v[128:129], v[148:149]
	v_pk_mul_f32 v[134:135], v[130:131], s[20:21] op_sel_hi:[1,0]
	v_pk_fma_f32 v[128:129], v[140:141], v[176:177], v[128:129]
	v_exp_f32_e32 v134, v134
	v_pk_fma_f32 v[128:129], v[136:137], v[132:133], v[128:129]
	v_exp_f32_e32 v135, v135
	v_pk_mul_f32 v[132:133], v[128:129], s[20:21] op_sel_hi:[1,0]
	v_pk_mul_f32 v[128:129], v[142:143], v[128:129]
	v_exp_f32_e32 v132, v132
	v_exp_f32_e32 v133, v133
	v_pk_add_f32 v[134:135], v[134:135], 1.0 op_sel_hi:[1,0]
	s_lshl_b32 s4, s56, 8
	v_rcp_f32_e32 v134, v134
	v_pk_add_f32 v[132:133], v[132:133], 1.0 op_sel_hi:[1,0]
	v_rcp_f32_e32 v135, v135
	v_rcp_f32_e32 v132, v132
	v_rcp_f32_e32 v133, v133
	v_pk_mul_f32 v[130:131], v[138:139], v[130:131]
	v_mov_b64_e32 v[148:149], s[60:61]
	s_movk_i32 s19, 0x1600
	v_pk_mul_f32 v[128:129], v[128:129], v[132:133]
	v_add_u32_e32 v132, s4, v208
	v_pk_mul_f32 v[130:131], v[130:131], v[134:135]
	v_mad_i64_i32 v[132:133], s[8:9], v132, s19, v[148:149]
	v_lshlrev_b64 v[150:151], 1, v[174:175]
	v_cvt_pk_bf16_f32 v128, v128, v129
	v_cvt_pk_bf16_f32 v129, v130, v131
	v_cvt_pk_bf16_f32 v130, v146, v147
	v_cvt_pk_bf16_f32 v131, v144, v145
	v_lshl_add_u64 v[132:133], v[132:133], 0, v[150:151]
	v_or_b32_e32 v147, 32, v160
	global_store_dwordx4 v[132:133], v[128:131], off
	v_mov_b32_e32 v173, v167
	s_nop 0
	v_lshl_add_u32 v128, v147, 3, s67
	ds_read_b64 v[128:129], v128
	s_waitcnt lgkmcnt(0)
	v_pk_mul_f32 v[136:137], v[128:129], s[96:97] op_sel_hi:[1,0]
	v_fma_f32 v128, -v136, v136, v137
	v_max_f32_e32 v128, 0, v128
	v_add_f32_e32 v128, 0x3727c5ac, v128
	v_rsq_f32_e32 v180, v128
	s_nop 0
	v_mul_f32_e64 v146, v180, -v136
	s_waitcnt lgkmcnt(0)
	v_pk_fma_f32 v[128:129], v[222:223], v[146:147], v[226:227] op_sel_hi:[1,0,1]
	v_pk_fma_f32 v[132:133], v[108:109], v[180:181], v[128:129] op_sel_hi:[1,0,1]
	v_pk_fma_f32 v[128:129], v[224:225], v[146:147], v[228:229] op_sel_hi:[1,0,1]
	v_pk_fma_f32 v[134:135], v[232:233], v[146:147], v[236:237] op_sel_hi:[1,0,1]
	v_pk_fma_f32 v[136:137], v[110:111], v[180:181], v[128:129] op_sel_hi:[1,0,1]
	v_pk_fma_f32 v[128:129], v[230:231], v[146:147], v[234:235] op_sel_hi:[1,0,1]
	v_pk_fma_f32 v[190:191], v[106:107], v[180:181], v[134:135] op_sel_hi:[1,0,1]
	v_pk_fma_f32 v[188:189], v[104:105], v[180:181], v[128:129] op_sel_hi:[1,0,1]
	s_nop 0
	v_mov_b32_dpp v219, v190 row_ror:2 row_mask:0xf bank_mask:0xf
	v_mov_b32_dpp v220, v191 row_ror:2 row_mask:0xf bank_mask:0xf
	v_mov_b32_dpp v217, v190 row_ror:1 row_mask:0xf bank_mask:0xf
	s_waitcnt lgkmcnt(0)
	v_pk_fma_f32 v[130:131], v[240:241], v[146:147], v[246:247] op_sel_hi:[1,0,1]
	v_pk_fma_f32 v[128:129], v[238:239], v[146:147], v[244:245] op_sel_hi:[1,0,1]
	v_pk_fma_f32 v[134:135], v[78:79], v[180:181], v[130:131] op_sel_hi:[1,0,1]
	v_pk_fma_f32 v[130:131], v[88:89], v[146:147], v[92:93] op_sel_hi:[1,0,1]
	v_pk_fma_f32 v[138:139], v[76:77], v[180:181], v[128:129] op_sel_hi:[1,0,1]
	v_pk_fma_f32 v[198:199], v[72:73], v[180:181], v[130:131] op_sel_hi:[1,0,1]
	v_pk_fma_f32 v[130:131], v[90:91], v[146:147], v[94:95] op_sel_hi:[1,0,1]
	v_pk_fma_f32 v[200:201], v[74:75], v[180:181], v[130:131] op_sel_hi:[1,0,1]
	ds_read_b128 v[80:83], v173 offset:1552
	ds_read_b128 v[84:87], v173 offset:528
	ds_read_b128 v[112:115], v173 offset:0
	v_mov_b32_dpp v218, v191 row_ror:1 row_mask:0xf bank_mask:0xf
	v_cndmask_b32_e32 v203, v213, v220, vcc
	v_cndmask_b32_e32 v202, v212, v219, vcc
	v_mov_b32_dpp v214, v189 row_ror:1 row_mask:0xf bank_mask:0xf
	v_mov_b32_dpp v215, v188 row_ror:2 row_mask:0xf bank_mask:0xf
	v_mov_b32_dpp v216, v189 row_ror:2 row_mask:0xf bank_mask:0xf
	v_cndmask_b32_e64 v181, v218, v211, s[42:43]
	v_cndmask_b32_e64 v180, v217, v210, s[42:43]
	s_waitcnt lgkmcnt(0)
	v_pk_fma_f32 v[178:179], v[202:203], v[126:127], v[82:83]
	v_mov_b32_dpp v209, v188 row_ror:1 row_mask:0xf bank_mask:0xf
	v_pk_fma_f32 v[178:179], v[180:181], v[86:87], v[178:179]
	v_cndmask_b32_e64 v181, v214, v164, s[42:43]
	v_cndmask_b32_e32 v165, v165, v216, vcc
	v_cndmask_b32_e32 v164, v163, v215, vcc
	v_cndmask_b32_e64 v180, v209, v162, s[42:43]
	v_pk_fma_f32 v[162:163], v[164:165], v[124:125], v[80:81]
	v_pk_fma_f32 v[142:143], v[190:191], v[122:123], v[178:179]
	v_pk_fma_f32 v[162:163], v[180:181], v[84:85], v[162:163]
	v_pk_mul_f32 v[178:179], v[142:143], s[20:21] op_sel_hi:[1,0]
	v_pk_fma_f32 v[162:163], v[188:189], v[120:121], v[162:163]
	v_exp_f32_e32 v178, v178
	v_pk_mul_f32 v[140:141], v[162:163], s[20:21] op_sel_hi:[1,0]
	v_exp_f32_e32 v179, v179
	v_exp_f32_e32 v140, v140
	v_exp_f32_e32 v141, v141
	v_pk_add_f32 v[164:165], v[178:179], 1.0 op_sel_hi:[1,0]
	v_pk_add_f32 v[140:141], v[140:141], 1.0 op_sel_hi:[1,0]
	v_rcp_f32_e32 v164, v164
	v_rcp_f32_e32 v165, v165
	v_rcp_f32_e32 v176, v140
	v_rcp_f32_e32 v177, v141
	v_pk_mul_f32 v[140:141], v[200:201], v[142:143]
	v_pk_mul_f32 v[142:143], v[198:199], v[162:163]
	v_pk_mul_f32 v[140:141], v[140:141], v[164:165]
	v_pk_mul_f32 v[142:143], v[142:143], v[176:177]
	ds_read_b128 v[116:119], v173 offset:1024
	ds_read_b128 v[176:179], v173 offset:1536
	ds_read_b128 v[184:187], v173 offset:512
	v_mov_b32_dpp v146, v133 row_ror:1 row_mask:0xf bank_mask:0xf
	v_mov_b32_dpp v145, v132 row_ror:2 row_mask:0xf bank_mask:0xf
	v_mov_b32_dpp v204, v133 row_ror:2 row_mask:0xf bank_mask:0xf
	v_mov_b32_dpp v206, v137 row_ror:1 row_mask:0xf bank_mask:0xf
	v_mov_b32_dpp v207, v136 row_ror:2 row_mask:0xf bank_mask:0xf
	v_mov_b32_dpp v208, v137 row_ror:2 row_mask:0xf bank_mask:0xf
	v_mov_b32_dpp v144, v132 row_ror:1 row_mask:0xf bank_mask:0xf
	v_mov_b32_dpp v205, v136 row_ror:1 row_mask:0xf bank_mask:0xf
	v_cndmask_b32_e64 v181, v206, v159, s[42:43]
	v_cndmask_b32_e32 v159, v158, v208, vcc
	v_cndmask_b32_e32 v158, v157, v207, vcc
	v_cndmask_b32_e64 v157, v146, v154, s[42:43]
	v_cndmask_b32_e32 v155, v155, v204, vcc
	v_cndmask_b32_e32 v154, v153, v145, vcc
	v_cndmask_b32_e64 v180, v205, v156, s[42:43]
	v_cndmask_b32_e64 v156, v144, v152, s[42:43]
	s_waitcnt lgkmcnt(0)
	v_pk_fma_f32 v[128:129], v[154:155], v[112:113], v[176:177]
	v_pk_fma_f32 v[130:131], v[158:159], v[114:115], v[178:179]
	v_pk_fma_f32 v[128:129], v[156:157], v[184:185], v[128:129]
	v_pk_fma_f32 v[130:131], v[180:181], v[186:187], v[130:131]
	v_pk_fma_f32 v[128:129], v[132:133], v[116:117], v[128:129]
	v_pk_fma_f32 v[130:131], v[136:137], v[118:119], v[130:131]
	v_pk_mul_f32 v[132:133], v[128:129], s[20:21] op_sel_hi:[1,0]
	v_pk_mul_f32 v[136:137], v[130:131], s[20:21] op_sel_hi:[1,0]
	v_exp_f32_e32 v132, v132
	v_exp_f32_e32 v133, v133
	v_exp_f32_e32 v136, v136
	v_exp_f32_e32 v137, v137
	v_pk_mul_f32 v[128:129], v[138:139], v[128:129]
	v_pk_add_f32 v[132:133], v[132:133], 1.0 op_sel_hi:[1,0]
	v_pk_mul_f32 v[130:131], v[134:135], v[130:131]
	v_pk_add_f32 v[136:137], v[136:137], 1.0 op_sel_hi:[1,0]
	v_rcp_f32_e32 v132, v132
	v_rcp_f32_e32 v133, v133
	v_rcp_f32_e32 v136, v136
	v_rcp_f32_e32 v137, v137
	v_or_b32_e32 v173, 48, v160
	v_pk_mul_f32 v[128:129], v[128:129], v[132:133]
	v_add_u32_e32 v132, s4, v147
	v_pk_mul_f32 v[130:131], v[130:131], v[136:137]
	v_mad_i64_i32 v[132:133], s[8:9], v132, s19, v[148:149]
	v_cvt_pk_bf16_f32 v128, v128, v129
	v_cvt_pk_bf16_f32 v129, v130, v131
	v_cvt_pk_bf16_f32 v130, v142, v143
	v_cvt_pk_bf16_f32 v131, v140, v141
	v_lshl_add_u64 v[132:133], v[132:133], 0, v[150:151]
	global_store_dwordx4 v[132:133], v[128:131], off
	v_mov_b32_e32 v147, v167
	s_nop 0
	v_lshl_add_u32 v128, v173, 3, s67
	ds_read_b64 v[128:129], v128
	s_waitcnt lgkmcnt(0)
	v_pk_mul_f32 v[142:143], v[128:129], s[96:97] op_sel_hi:[1,0]
	v_fma_f32 v128, -v142, v142, v143
	v_max_f32_e32 v128, 0, v128
	v_add_f32_e32 v128, 0x3727c5ac, v128
	v_rsq_f32_e32 v156, v128
	s_nop 0
	v_mul_f32_e64 v142, v156, -v142
	v_pk_fma_f32 v[130:131], v[222:223], v[142:143], v[226:227] op_sel_hi:[1,0,1]
	v_pk_fma_f32 v[158:159], v[232:233], v[142:143], v[236:237] op_sel_hi:[1,0,1]
	v_pk_fma_f32 v[162:163], v[100:101], v[156:157], v[130:131] op_sel_hi:[1,0,1]
	v_pk_fma_f32 v[130:131], v[224:225], v[142:143], v[228:229] op_sel_hi:[1,0,1]
	v_pk_fma_f32 v[178:179], v[98:99], v[156:157], v[158:159] op_sel_hi:[1,0,1]
	v_pk_fma_f32 v[164:165], v[102:103], v[156:157], v[130:131] op_sel_hi:[1,0,1]
	v_pk_fma_f32 v[130:131], v[230:231], v[142:143], v[234:235] op_sel_hi:[1,0,1]
	v_mov_b32_dpp v190, v178 row_ror:2 row_mask:0xf bank_mask:0xf
	v_pk_fma_f32 v[176:177], v[96:97], v[156:157], v[130:131] op_sel_hi:[1,0,1]
	v_mov_b32_dpp v191, v179 row_ror:2 row_mask:0xf bank_mask:0xf
	v_cndmask_b32_e32 v191, v220, v191, vcc
	v_cndmask_b32_e32 v190, v219, v190, vcc
	s_waitcnt lgkmcnt(0)
	v_pk_fma_f32 v[132:133], v[240:241], v[142:143], v[246:247] op_sel_hi:[1,0,1]
	v_pk_fma_f32 v[130:131], v[238:239], v[142:143], v[244:245] op_sel_hi:[1,0,1]
	v_pk_fma_f32 v[180:181], v[70:71], v[156:157], v[132:133] op_sel_hi:[1,0,1]
	v_pk_fma_f32 v[132:133], v[88:89], v[142:143], v[92:93] op_sel_hi:[1,0,1]
	v_pk_fma_f32 v[184:185], v[64:65], v[156:157], v[132:133] op_sel_hi:[1,0,1]
	v_pk_fma_f32 v[132:133], v[90:91], v[142:143], v[94:95] op_sel_hi:[1,0,1]
	v_mov_b32_dpp v134, v178 row_ror:1 row_mask:0xf bank_mask:0xf
	v_mov_b32_dpp v135, v179 row_ror:1 row_mask:0xf bank_mask:0xf
	v_pk_fma_f32 v[142:143], v[66:67], v[156:157], v[132:133] op_sel_hi:[1,0,1]
	v_pk_fma_f32 v[186:187], v[68:69], v[156:157], v[130:131] op_sel_hi:[1,0,1]
	v_cndmask_b32_e64 v189, v135, v218, s[42:43]
	v_cndmask_b32_e64 v188, v134, v217, s[42:43]
	v_mov_b32_dpp v203, v176 row_ror:2 row_mask:0xf bank_mask:0xf
	v_mov_b32_dpp v210, v177 row_ror:2 row_mask:0xf bank_mask:0xf
	s_waitcnt lgkmcnt(0)
	v_pk_fma_f32 v[136:137], v[190:191], v[126:127], v[82:83]
	v_mov_b32_dpp v201, v176 row_ror:1 row_mask:0xf bank_mask:0xf
	v_mov_b32_dpp v202, v177 row_ror:1 row_mask:0xf bank_mask:0xf
	v_pk_fma_f32 v[136:137], v[188:189], v[86:87], v[136:137]
	v_cndmask_b32_e32 v155, v216, v210, vcc
	v_cndmask_b32_e32 v154, v215, v203, vcc
	v_cndmask_b32_e64 v141, v202, v214, s[42:43]
	v_cndmask_b32_e64 v140, v201, v209, s[42:43]
	v_pk_fma_f32 v[134:135], v[154:155], v[124:125], v[80:81]
	v_pk_fma_f32 v[132:133], v[178:179], v[122:123], v[136:137]
	v_pk_fma_f32 v[134:135], v[140:141], v[84:85], v[134:135]
	v_pk_mul_f32 v[136:137], v[132:133], s[20:21] op_sel_hi:[1,0]
	v_pk_fma_f32 v[130:131], v[176:177], v[120:121], v[134:135]
	v_exp_f32_e32 v136, v136
	v_pk_mul_f32 v[134:135], v[130:131], s[20:21] op_sel_hi:[1,0]
	v_exp_f32_e32 v137, v137
	v_exp_f32_e32 v134, v134
	v_exp_f32_e32 v135, v135
	v_pk_mul_f32 v[132:133], v[142:143], v[132:133]
	v_pk_add_f32 v[136:137], v[136:137], 1.0 op_sel_hi:[1,0]
	v_pk_mul_f32 v[130:131], v[184:185], v[130:131]
	v_pk_add_f32 v[134:135], v[134:135], 1.0 op_sel_hi:[1,0]
	v_rcp_f32_e32 v136, v136
	v_rcp_f32_e32 v137, v137
	v_rcp_f32_e32 v134, v134
	v_rcp_f32_e32 v135, v135
	v_pk_mul_f32 v[142:143], v[132:133], v[136:137]
	v_pk_mul_f32 v[152:153], v[130:131], v[134:135]
	ds_read_b128 v[72:75], v147 offset:1536
	ds_read_b128 v[76:79], v147 offset:512
	v_mov_b32_dpp v199, v164 row_ror:2 row_mask:0xf bank_mask:0xf
	v_mov_b32_dpp v200, v165 row_ror:2 row_mask:0xf bank_mask:0xf
	v_mov_b32_dpp v197, v164 row_ror:1 row_mask:0xf bank_mask:0xf
	v_mov_b32_dpp v198, v165 row_ror:1 row_mask:0xf bank_mask:0xf
	v_cndmask_b32_e32 v177, v208, v200, vcc
	v_cndmask_b32_e32 v176, v207, v199, vcc
	v_mov_b32_dpp v194, v163 row_ror:1 row_mask:0xf bank_mask:0xf
	v_mov_b32_dpp v195, v162 row_ror:2 row_mask:0xf bank_mask:0xf
	v_mov_b32_dpp v196, v163 row_ror:2 row_mask:0xf bank_mask:0xf
	v_cndmask_b32_e64 v155, v198, v206, s[42:43]
	v_cndmask_b32_e64 v154, v197, v205, s[42:43]
	s_waitcnt lgkmcnt(0)
	v_pk_fma_f32 v[136:137], v[176:177], v[114:115], v[74:75]
	v_mov_b32_dpp v129, v162 row_ror:1 row_mask:0xf bank_mask:0xf
	v_pk_fma_f32 v[136:137], v[154:155], v[78:79], v[136:137]
	v_cndmask_b32_e64 v141, v194, v146, s[42:43]
	v_cndmask_b32_e32 v147, v204, v196, vcc
	v_cndmask_b32_e32 v146, v145, v195, vcc
	v_cndmask_b32_e64 v140, v129, v144, s[42:43]
	v_pk_fma_f32 v[134:135], v[146:147], v[112:113], v[72:73]
	v_pk_fma_f32 v[132:133], v[164:165], v[118:119], v[136:137]
	v_pk_fma_f32 v[134:135], v[140:141], v[76:77], v[134:135]
	v_pk_mul_f32 v[136:137], v[132:133], s[20:21] op_sel_hi:[1,0]
	v_pk_fma_f32 v[130:131], v[162:163], v[116:117], v[134:135]
	v_exp_f32_e32 v136, v136
	v_pk_mul_f32 v[134:135], v[130:131], s[20:21] op_sel_hi:[1,0]
	v_exp_f32_e32 v137, v137
	v_exp_f32_e32 v134, v134
	v_exp_f32_e32 v135, v135
	s_xor_b64 s[8:9], s[48:49], -1
	v_pk_add_f32 v[136:137], v[136:137], 1.0 op_sel_hi:[1,0]
	v_cndmask_b32_e64 v128, 0, 1, s[8:9]
	v_pk_add_f32 v[134:135], v[134:135], 1.0 op_sel_hi:[1,0]
	v_rcp_f32_e32 v136, v136
	v_rcp_f32_e32 v137, v137
	v_rcp_f32_e32 v134, v134
	v_rcp_f32_e32 v135, v135
	s_and_b64 s[8:9], s[48:49], exec
	s_cselect_b32 s5, 2, 0
	v_or_b32_e32 v128, s5, v128
	v_pk_mul_f32 v[132:133], v[180:181], v[132:133]
	v_pk_mul_f32 v[130:131], v[186:187], v[130:131]
	v_add_u32_e32 v129, s4, v173
	v_lshlrev_b32_e32 v128, 10, v128
	v_pk_mul_f32 v[132:133], v[132:133], v[136:137]
	v_pk_mul_f32 v[130:131], v[130:131], v[134:135]
	v_mad_i64_i32 v[134:135], s[8:9], v129, s19, v[148:149]
	v_add_u32_e32 v128, 0, v128
	v_cvt_pk_bf16_f32 v130, v130, v131
	v_cvt_pk_bf16_f32 v131, v132, v133
	v_cvt_pk_bf16_f32 v132, v152, v153
	v_cvt_pk_bf16_f32 v133, v142, v143
	v_lshl_add_u64 v[134:135], v[134:135], 0, v[150:151]
	v_lshl_add_u32 v128, v171, 2, v128
	global_store_dwordx4 v[134:135], v[130:133], off
	v_add_u32_e32 v136, 0x20000, v128
	v_add_u32_e32 v214, 0x80, v160
	ds_read_b128 v[128:131], v136
	ds_read_b128 v[140:143], v136 offset:16
	ds_read_b128 v[132:135], v136 offset:512
	ds_read_b128 v[144:147], v136 offset:528
	v_mov_b32_e32 v215, v167
	v_lshl_add_u32 v136, v214, 3, s67
	ds_read_b64 v[136:137], v136
	s_waitcnt lgkmcnt(0)
	v_pk_mul_f32 v[156:157], v[136:137], s[96:97] op_sel_hi:[1,0]
	v_cndmask_b32_e64 v142, v142, v146, s[44:45]
	v_fma_f32 v136, -v156, v156, v157
	v_max_f32_e32 v136, 0, v136
	v_add_f32_e32 v136, 0x3727c5ac, v136
	v_rsq_f32_e32 v158, v136
	v_cndmask_b32_e64 v143, v143, v147, s[44:45]
	v_cndmask_b32_e64 v140, v140, v144, s[44:45]
	v_mul_f32_e64 v180, v158, -v156
	s_waitcnt lgkmcnt(0)
	v_pk_fma_f32 v[136:137], v[222:223], v[180:181], v[226:227] op_sel_hi:[1,0,1]
	v_cndmask_b32_e64 v141, v141, v145, s[44:45]
	v_pk_fma_f32 v[152:153], v[60:61], v[158:159], v[136:137] op_sel_hi:[1,0,1]
	v_pk_fma_f32 v[136:137], v[224:225], v[180:181], v[228:229] op_sel_hi:[1,0,1]
	v_pk_fma_f32 v[154:155], v[232:233], v[180:181], v[236:237] op_sel_hi:[1,0,1]
	v_pk_fma_f32 v[156:157], v[62:63], v[158:159], v[136:137] op_sel_hi:[1,0,1]
	v_pk_fma_f32 v[136:137], v[230:231], v[180:181], v[234:235] op_sel_hi:[1,0,1]
	v_pk_fma_f32 v[206:207], v[58:59], v[158:159], v[154:155] op_sel_hi:[1,0,1]
	v_pk_fma_f32 v[190:191], v[56:57], v[158:159], v[136:137] op_sel_hi:[1,0,1]
	s_nop 0
	v_mov_b32_dpp v188, v206 row_ror:2 row_mask:0xf bank_mask:0xf
	v_mov_b32_dpp v189, v207 row_ror:2 row_mask:0xf bank_mask:0xf
	v_mov_b32_dpp v216, v206 row_ror:1 row_mask:0xf bank_mask:0xf
	s_waitcnt lgkmcnt(0)
	v_pk_fma_f32 v[138:139], v[240:241], v[180:181], v[246:247] op_sel_hi:[1,0,1]
	v_pk_fma_f32 v[136:137], v[238:239], v[180:181], v[244:245] op_sel_hi:[1,0,1]
	v_pk_fma_f32 v[154:155], v[30:31], v[158:159], v[138:139] op_sel_hi:[1,0,1]
	v_pk_fma_f32 v[138:139], v[88:89], v[180:181], v[92:93] op_sel_hi:[1,0,1]
	v_pk_fma_f32 v[208:209], v[24:25], v[158:159], v[138:139] op_sel_hi:[1,0,1]
	v_pk_fma_f32 v[138:139], v[90:91], v[180:181], v[94:95] op_sel_hi:[1,0,1]
	v_pk_fma_f32 v[210:211], v[26:27], v[158:159], v[138:139] op_sel_hi:[1,0,1]
	v_pk_fma_f32 v[158:159], v[28:29], v[158:159], v[136:137] op_sel_hi:[1,0,1]
	v_mov_b32_dpp v217, v207 row_ror:1 row_mask:0xf bank_mask:0xf
	v_cndmask_b32_e32 v143, v143, v189, vcc
	v_cndmask_b32_e32 v142, v142, v188, vcc
	v_mov_b32_dpp v185, v190 row_ror:2 row_mask:0xf bank_mask:0xf
	v_mov_b32_dpp v187, v191 row_ror:2 row_mask:0xf bank_mask:0xf
	v_cndmask_b32_e64 v213, v217, v147, s[42:43]
	v_cndmask_b32_e64 v212, v216, v146, s[42:43]
	s_waitcnt lgkmcnt(0)
	v_pk_fma_f32 v[142:143], v[142:143], v[126:127], v[82:83]
	v_mov_b32_dpp v184, v190 row_ror:1 row_mask:0xf bank_mask:0xf
	v_mov_b32_dpp v186, v191 row_ror:1 row_mask:0xf bank_mask:0xf
	v_pk_fma_f32 v[142:143], v[212:213], v[86:87], v[142:143]
	v_cndmask_b32_e32 v141, v141, v187, vcc
	v_cndmask_b32_e32 v140, v140, v185, vcc
	v_pk_fma_f32 v[142:143], v[206:207], v[122:123], v[142:143]
	v_cndmask_b32_e64 v165, v186, v145, s[42:43]
	v_cndmask_b32_e64 v164, v184, v144, s[42:43]
	v_pk_fma_f32 v[140:141], v[140:141], v[124:125], v[80:81]
	v_pk_mul_f32 v[146:147], v[142:143], s[20:21] op_sel_hi:[1,0]
	v_pk_fma_f32 v[140:141], v[164:165], v[84:85], v[140:141]
	v_exp_f32_e32 v146, v146
	v_pk_fma_f32 v[140:141], v[190:191], v[120:121], v[140:141]
	v_exp_f32_e32 v147, v147
	v_pk_mul_f32 v[144:145], v[140:141], s[20:21] op_sel_hi:[1,0]
	v_pk_mul_f32 v[142:143], v[210:211], v[142:143]
	v_exp_f32_e32 v144, v144
	v_exp_f32_e32 v145, v145
	v_pk_add_f32 v[146:147], v[146:147], 1.0 op_sel_hi:[1,0]
	v_pk_mul_f32 v[140:141], v[208:209], v[140:141]
	v_rcp_f32_e32 v146, v146
	v_pk_add_f32 v[144:145], v[144:145], 1.0 op_sel_hi:[1,0]
	v_rcp_f32_e32 v147, v147
	v_rcp_f32_e32 v144, v144
	v_rcp_f32_e32 v145, v145
	v_pk_mul_f32 v[162:163], v[142:143], v[146:147]
	v_pk_mul_f32 v[164:165], v[140:141], v[144:145]
	v_mov_b32_dpp v173, v152 row_ror:2 row_mask:0xf bank_mask:0xf
	v_mov_b32_dpp v177, v153 row_ror:2 row_mask:0xf bank_mask:0xf
	v_mov_b32_dpp v179, v156 row_ror:2 row_mask:0xf bank_mask:0xf
	v_mov_b32_dpp v180, v157 row_ror:2 row_mask:0xf bank_mask:0xf
	v_cndmask_b32_e64 v130, v130, v134, s[44:45]
	v_cndmask_b32_e64 v131, v131, v135, s[44:45]
	v_cndmask_b32_e64 v128, v128, v132, s[44:45]
	v_cndmask_b32_e64 v129, v129, v133, s[44:45]
	v_mov_b32_dpp v171, v152 row_ror:1 row_mask:0xf bank_mask:0xf
	v_mov_b32_dpp v176, v153 row_ror:1 row_mask:0xf bank_mask:0xf
	v_cndmask_b32_e32 v131, v131, v180, vcc
	v_cndmask_b32_e32 v130, v130, v179, vcc
	v_cndmask_b32_e32 v129, v129, v177, vcc
	v_cndmask_b32_e32 v128, v128, v173, vcc
	v_mov_b32_dpp v178, v156 row_ror:1 row_mask:0xf bank_mask:0xf
	v_mov_b32_dpp v181, v157 row_ror:1 row_mask:0xf bank_mask:0xf
	s_waitcnt lgkmcnt(0)
	v_pk_fma_f32 v[130:131], v[130:131], v[114:115], v[74:75]
	v_cndmask_b32_e64 v139, v176, v133, s[42:43]
	v_cndmask_b32_e64 v138, v171, v132, s[42:43]
	v_pk_fma_f32 v[128:129], v[128:129], v[112:113], v[72:73]
	v_cndmask_b32_e64 v191, v181, v135, s[42:43]
	v_cndmask_b32_e64 v190, v178, v134, s[42:43]
	v_pk_fma_f32 v[128:129], v[138:139], v[76:77], v[128:129]
	v_pk_fma_f32 v[130:131], v[190:191], v[78:79], v[130:131]
	v_pk_fma_f32 v[128:129], v[152:153], v[116:117], v[128:129]
	v_pk_fma_f32 v[130:131], v[156:157], v[118:119], v[130:131]
	v_pk_mul_f32 v[132:133], v[128:129], s[20:21] op_sel_hi:[1,0]
	v_pk_mul_f32 v[134:135], v[130:131], s[20:21] op_sel_hi:[1,0]
	v_exp_f32_e32 v132, v132
	v_exp_f32_e32 v133, v133
	v_exp_f32_e32 v134, v134
	v_exp_f32_e32 v135, v135
	v_pk_mul_f32 v[128:129], v[158:159], v[128:129]
	v_pk_add_f32 v[132:133], v[132:133], 1.0 op_sel_hi:[1,0]
	v_pk_mul_f32 v[130:131], v[154:155], v[130:131]
	v_pk_add_f32 v[134:135], v[134:135], 1.0 op_sel_hi:[1,0]
	v_rcp_f32_e32 v132, v132
	v_rcp_f32_e32 v133, v133
	v_rcp_f32_e32 v134, v134
	v_rcp_f32_e32 v135, v135
	v_add_u32_e32 v208, 0x90, v160
	v_pk_mul_f32 v[128:129], v[128:129], v[132:133]
	v_add_u32_e32 v132, s4, v214
	v_pk_mul_f32 v[130:131], v[130:131], v[134:135]
	v_mad_i64_i32 v[132:133], s[8:9], v132, s19, v[148:149]
	v_cvt_pk_bf16_f32 v128, v128, v129
	v_cvt_pk_bf16_f32 v129, v130, v131
	v_cvt_pk_bf16_f32 v130, v164, v165
	v_cvt_pk_bf16_f32 v131, v162, v163
	v_lshl_add_u64 v[132:133], v[132:133], 0, v[150:151]
	global_store_dwordx4 v[132:133], v[128:131], off
	v_mov_b32_e32 v209, v167
	s_nop 0
	v_lshl_add_u32 v128, v208, 3, s67
	ds_read_b64 v[128:129], v128
	s_waitcnt lgkmcnt(0)
	v_pk_mul_f32 v[136:137], v[128:129], s[96:97] op_sel_hi:[1,0]
	v_fma_f32 v128, -v136, v136, v137
	v_max_f32_e32 v128, 0, v128
	v_add_f32_e32 v128, 0x3727c5ac, v128
	v_rsq_f32_e32 v156, v128
	s_nop 0
	v_mul_f32_e64 v146, v156, -v136
	s_waitcnt lgkmcnt(0)
	v_pk_fma_f32 v[128:129], v[222:223], v[146:147], v[226:227] op_sel_hi:[1,0,1]
	v_mov_b32_e32 v218, v161
	v_pk_fma_f32 v[132:133], v[52:53], v[156:157], v[128:129] op_sel_hi:[1,0,1]
	v_pk_fma_f32 v[128:129], v[224:225], v[146:147], v[228:229] op_sel_hi:[1,0,1]
	v_pk_fma_f32 v[134:135], v[232:233], v[146:147], v[236:237] op_sel_hi:[1,0,1]
	v_pk_fma_f32 v[136:137], v[54:55], v[156:157], v[128:129] op_sel_hi:[1,0,1]
	v_pk_fma_f32 v[128:129], v[230:231], v[146:147], v[234:235] op_sel_hi:[1,0,1]
	v_pk_fma_f32 v[200:201], v[50:51], v[156:157], v[134:135] op_sel_hi:[1,0,1]
	v_pk_fma_f32 v[190:191], v[48:49], v[156:157], v[128:129] op_sel_hi:[1,0,1]
	s_nop 0
	v_mov_b32_dpp v214, v200 row_ror:2 row_mask:0xf bank_mask:0xf
	v_mov_b32_dpp v215, v201 row_ror:2 row_mask:0xf bank_mask:0xf
	v_mov_b32_dpp v210, v191 row_ror:1 row_mask:0xf bank_mask:0xf
	s_waitcnt lgkmcnt(0)
	v_pk_fma_f32 v[130:131], v[240:241], v[146:147], v[246:247] op_sel_hi:[1,0,1]
	v_pk_fma_f32 v[128:129], v[238:239], v[146:147], v[244:245] op_sel_hi:[1,0,1]
	v_pk_fma_f32 v[134:135], v[22:23], v[156:157], v[130:131] op_sel_hi:[1,0,1]
	v_pk_fma_f32 v[130:131], v[88:89], v[146:147], v[92:93] op_sel_hi:[1,0,1]
	v_pk_fma_f32 v[138:139], v[20:21], v[156:157], v[128:129] op_sel_hi:[1,0,1]
	v_pk_fma_f32 v[202:203], v[16:17], v[156:157], v[130:131] op_sel_hi:[1,0,1]
	v_pk_fma_f32 v[130:131], v[90:91], v[146:147], v[94:95] op_sel_hi:[1,0,1]
	v_pk_fma_f32 v[204:205], v[18:19], v[156:157], v[130:131] op_sel_hi:[1,0,1]
	v_mov_b32_dpp v195, v190 row_ror:2 row_mask:0xf bank_mask:0xf
	v_mov_b32_dpp v211, v191 row_ror:2 row_mask:0xf bank_mask:0xf
	v_cndmask_b32_e32 v189, v189, v215, vcc
	v_cndmask_b32_e32 v188, v188, v214, vcc
	v_mov_b32_dpp v194, v190 row_ror:1 row_mask:0xf bank_mask:0xf
	v_mov_b32_dpp v212, v200 row_ror:1 row_mask:0xf bank_mask:0xf
	v_mov_b32_dpp v213, v201 row_ror:1 row_mask:0xf bank_mask:0xf
	s_waitcnt lgkmcnt(0)
	v_pk_fma_f32 v[158:159], v[188:189], v[126:127], v[82:83]
	v_cndmask_b32_e64 v165, v210, v186, s[42:43]
	v_cndmask_b32_e32 v187, v187, v211, vcc
	v_cndmask_b32_e32 v186, v185, v195, vcc
	v_cndmask_b32_e64 v207, v213, v217, s[42:43]
	v_cndmask_b32_e64 v206, v212, v216, s[42:43]
	v_cndmask_b32_e64 v164, v194, v184, s[42:43]
	v_pk_fma_f32 v[156:157], v[186:187], v[124:125], v[80:81]
	v_pk_fma_f32 v[158:159], v[206:207], v[86:87], v[158:159]
	v_pk_fma_f32 v[156:157], v[164:165], v[84:85], v[156:157]
	v_pk_fma_f32 v[142:143], v[200:201], v[122:123], v[158:159]
	v_pk_fma_f32 v[156:157], v[190:191], v[120:121], v[156:157]
	v_pk_mul_f32 v[158:159], v[142:143], s[20:21] op_sel_hi:[1,0]
	v_pk_mul_f32 v[140:141], v[156:157], s[20:21] op_sel_hi:[1,0]
	v_exp_f32_e32 v158, v158
	v_exp_f32_e32 v159, v159
	v_exp_f32_e32 v140, v140
	v_exp_f32_e32 v141, v141
	v_pk_add_f32 v[158:159], v[158:159], 1.0 op_sel_hi:[1,0]
	v_pk_add_f32 v[140:141], v[140:141], 1.0 op_sel_hi:[1,0]
	v_rcp_f32_e32 v158, v158
	v_rcp_f32_e32 v159, v159
	v_rcp_f32_e32 v162, v140
	v_rcp_f32_e32 v163, v141
	v_pk_mul_f32 v[140:141], v[204:205], v[142:143]
	v_pk_mul_f32 v[142:143], v[202:203], v[156:157]
	v_pk_mul_f32 v[140:141], v[140:141], v[158:159]
	v_pk_mul_f32 v[142:143], v[142:143], v[162:163]
	v_mov_b32_dpp v155, v137 row_ror:1 row_mask:0xf bank_mask:0xf
	v_mov_b32_dpp v153, v136 row_ror:2 row_mask:0xf bank_mask:0xf
	v_mov_b32_dpp v154, v137 row_ror:2 row_mask:0xf bank_mask:0xf
	v_mov_b32_dpp v152, v136 row_ror:1 row_mask:0xf bank_mask:0xf
	v_cndmask_b32_e64 v189, v155, v181, s[42:43]
	v_cndmask_b32_e32 v181, v180, v154, vcc
	v_cndmask_b32_e32 v180, v179, v153, vcc
	v_mov_b32_dpp v145, v132 row_ror:2 row_mask:0xf bank_mask:0xf
	v_mov_b32_dpp v147, v133 row_ror:2 row_mask:0xf bank_mask:0xf
	v_cndmask_b32_e64 v188, v152, v178, s[42:43]
	s_waitcnt lgkmcnt(0)
	v_pk_fma_f32 v[130:131], v[180:181], v[114:115], v[74:75]
	v_mov_b32_dpp v144, v132 row_ror:1 row_mask:0xf bank_mask:0xf
	v_mov_b32_dpp v146, v133 row_ror:1 row_mask:0xf bank_mask:0xf
	v_pk_fma_f32 v[130:131], v[188:189], v[78:79], v[130:131]
	v_cndmask_b32_e32 v165, v177, v147, vcc
	v_cndmask_b32_e32 v164, v173, v145, vcc
	v_pk_fma_f32 v[130:131], v[136:137], v[118:119], v[130:131]
	v_cndmask_b32_e64 v159, v146, v176, s[42:43]
	v_cndmask_b32_e64 v158, v144, v171, s[42:43]
	v_pk_fma_f32 v[128:129], v[164:165], v[112:113], v[72:73]
	v_pk_mul_f32 v[136:137], v[130:131], s[20:21] op_sel_hi:[1,0]
	v_pk_fma_f32 v[128:129], v[158:159], v[76:77], v[128:129]
	v_exp_f32_e32 v136, v136
	v_pk_fma_f32 v[128:129], v[132:133], v[116:117], v[128:129]
	v_exp_f32_e32 v137, v137
	v_pk_mul_f32 v[132:133], v[128:129], s[20:21] op_sel_hi:[1,0]
	v_pk_mul_f32 v[128:129], v[138:139], v[128:129]
	v_exp_f32_e32 v132, v132
	v_exp_f32_e32 v133, v133
	v_pk_add_f32 v[136:137], v[136:137], 1.0 op_sel_hi:[1,0]
	v_pk_mul_f32 v[130:131], v[134:135], v[130:131]
	v_rcp_f32_e32 v136, v136
	v_pk_add_f32 v[132:133], v[132:133], 1.0 op_sel_hi:[1,0]
	v_rcp_f32_e32 v137, v137
	v_rcp_f32_e32 v132, v132
	v_rcp_f32_e32 v133, v133
	v_add_u32_e32 v179, 0xa0, v160
	v_pk_mul_f32 v[130:131], v[130:131], v[136:137]
	v_mov_b32_e32 v216, v167
	v_pk_mul_f32 v[128:129], v[128:129], v[132:133]
	v_add_u32_e32 v132, s4, v208
	v_mad_i64_i32 v[132:133], s[8:9], v132, s19, v[148:149]
	v_cvt_pk_bf16_f32 v128, v128, v129
	v_cvt_pk_bf16_f32 v129, v130, v131
	v_cvt_pk_bf16_f32 v130, v142, v143
	v_cvt_pk_bf16_f32 v131, v140, v141
	v_lshl_add_u64 v[132:133], v[132:133], 0, v[150:151]
	global_store_dwordx4 v[132:133], v[128:131], off
	s_nop 1
	v_lshl_add_u32 v128, v179, 3, s67
	ds_read_b64 v[128:129], v128
	s_and_b64 s[24:25], s[86:87], s[48:49]
	s_waitcnt lgkmcnt(0)
	v_pk_mul_f32 v[136:137], v[128:129], s[96:97] op_sel_hi:[1,0]
	s_nop 0
	v_fma_f32 v128, -v136, v136, v137
	v_max_f32_e32 v128, 0, v128
	v_add_f32_e32 v128, 0x3727c5ac, v128
	v_rsq_f32_e32 v142, v128
	s_nop 0
	v_mul_f32_e64 v176, v142, -v136
	s_waitcnt lgkmcnt(0)
	v_pk_fma_f32 v[128:129], v[222:223], v[176:177], v[226:227] op_sel_hi:[1,0,1]
	s_nop 0
	v_pk_fma_f32 v[132:133], v[44:45], v[142:143], v[128:129] op_sel_hi:[1,0,1]
	v_pk_fma_f32 v[128:129], v[224:225], v[176:177], v[228:229] op_sel_hi:[1,0,1]
	v_pk_fma_f32 v[134:135], v[232:233], v[176:177], v[236:237] op_sel_hi:[1,0,1]
	v_pk_fma_f32 v[136:137], v[46:47], v[142:143], v[128:129] op_sel_hi:[1,0,1]
	v_pk_fma_f32 v[128:129], v[230:231], v[176:177], v[234:235] op_sel_hi:[1,0,1]
	v_pk_fma_f32 v[188:189], v[42:43], v[142:143], v[134:135] op_sel_hi:[1,0,1]
	v_pk_fma_f32 v[180:181], v[40:41], v[142:143], v[128:129] op_sel_hi:[1,0,1]
	v_mov_b32_dpp v218, v133 row_ror:1 row_mask:0xf bank_mask:0xf
	v_mov_b32_dpp v219, v133 row_ror:2 row_mask:0xf bank_mask:0xf
	v_mov_b32_dpp v173, v136 row_ror:2 row_mask:0xf bank_mask:0xf
	s_waitcnt lgkmcnt(0)
	v_pk_fma_f32 v[130:131], v[240:241], v[176:177], v[246:247] op_sel_hi:[1,0,1]
	v_pk_fma_f32 v[128:129], v[238:239], v[176:177], v[244:245] op_sel_hi:[1,0,1]
	v_pk_fma_f32 v[134:135], v[14:15], v[142:143], v[130:131] op_sel_hi:[1,0,1]
	v_pk_fma_f32 v[130:131], v[88:89], v[176:177], v[92:93] op_sel_hi:[1,0,1]
	v_pk_fma_f32 v[190:191], v[8:9], v[142:143], v[130:131] op_sel_hi:[1,0,1]
	v_pk_fma_f32 v[130:131], v[90:91], v[176:177], v[94:95] op_sel_hi:[1,0,1]
	v_pk_fma_f32 v[204:205], v[10:11], v[142:143], v[130:131] op_sel_hi:[1,0,1]
	v_pk_fma_f32 v[138:139], v[12:13], v[142:143], v[128:129] op_sel_hi:[1,0,1]
	v_mov_b32_dpp v156, v188 row_ror:2 row_mask:0xf bank_mask:0xf
	v_mov_b32_dpp v157, v189 row_ror:2 row_mask:0xf bank_mask:0xf
	v_mov_b32_dpp v158, v188 row_ror:1 row_mask:0xf bank_mask:0xf
	v_mov_b32_dpp v159, v189 row_ror:1 row_mask:0xf bank_mask:0xf
	v_cndmask_b32_e32 v209, v215, v157, vcc
	v_cndmask_b32_e32 v208, v214, v156, vcc
	v_mov_b32_dpp v163, v180 row_ror:2 row_mask:0xf bank_mask:0xf
	v_mov_b32_dpp v164, v181 row_ror:2 row_mask:0xf bank_mask:0xf
	v_cndmask_b32_e64 v207, v159, v213, s[42:43]
	v_cndmask_b32_e64 v206, v158, v212, s[42:43]
	s_waitcnt lgkmcnt(0)
	v_pk_fma_f32 v[186:187], v[208:209], v[126:127], v[82:83]
	v_mov_b32_dpp v162, v180 row_ror:1 row_mask:0xf bank_mask:0xf
	v_mov_b32_dpp v165, v181 row_ror:1 row_mask:0xf bank_mask:0xf
	v_pk_fma_f32 v[186:187], v[206:207], v[86:87], v[186:187]
	v_cndmask_b32_e32 v199, v211, v164, vcc
	v_cndmask_b32_e32 v198, v195, v163, vcc
	v_pk_fma_f32 v[142:143], v[188:189], v[122:123], v[186:187]
	v_cndmask_b32_e64 v189, v165, v210, s[42:43]
	v_cndmask_b32_e64 v188, v162, v194, s[42:43]
	v_pk_fma_f32 v[184:185], v[198:199], v[124:125], v[80:81]
	v_pk_mul_f32 v[186:187], v[142:143], s[20:21] op_sel_hi:[1,0]
	v_pk_fma_f32 v[184:185], v[188:189], v[84:85], v[184:185]
	v_exp_f32_e32 v186, v186
	v_pk_fma_f32 v[180:181], v[180:181], v[120:121], v[184:185]
	v_exp_f32_e32 v187, v187
	v_pk_mul_f32 v[140:141], v[180:181], s[20:21] op_sel_hi:[1,0]
	v_exp_f32_e32 v140, v140
	v_exp_f32_e32 v141, v141
	v_pk_add_f32 v[184:185], v[186:187], 1.0 op_sel_hi:[1,0]
	v_rcp_f32_e32 v184, v184
	v_pk_add_f32 v[140:141], v[140:141], 1.0 op_sel_hi:[1,0]
	v_rcp_f32_e32 v185, v185
	v_rcp_f32_e32 v186, v140
	v_rcp_f32_e32 v187, v141
	v_pk_mul_f32 v[140:141], v[204:205], v[142:143]
	v_pk_mul_f32 v[142:143], v[190:191], v[180:181]
	v_pk_mul_f32 v[140:141], v[140:141], v[184:185]
	v_pk_mul_f32 v[142:143], v[142:143], v[186:187]
	v_mov_b32_dpp v177, v132 row_ror:2 row_mask:0xf bank_mask:0xf
	v_mov_b32_dpp v176, v137 row_ror:1 row_mask:0xf bank_mask:0xf
	v_mov_b32_dpp v178, v137 row_ror:2 row_mask:0xf bank_mask:0xf
	v_mov_b32_dpp v217, v132 row_ror:1 row_mask:0xf bank_mask:0xf
	v_mov_b32_dpp v171, v136 row_ror:1 row_mask:0xf bank_mask:0xf
	v_cndmask_b32_e64 v181, v176, v155, s[42:43]
	v_cndmask_b32_e32 v155, v154, v178, vcc
	v_cndmask_b32_e32 v154, v153, v173, vcc
	v_cndmask_b32_e64 v153, v218, v146, s[42:43]
	v_cndmask_b32_e32 v147, v147, v219, vcc
	v_cndmask_b32_e32 v146, v145, v177, vcc
	v_cndmask_b32_e64 v180, v171, v152, s[42:43]
	v_cndmask_b32_e64 v152, v217, v144, s[42:43]
	s_waitcnt lgkmcnt(0)
	v_pk_fma_f32 v[128:129], v[146:147], v[112:113], v[72:73]
	v_pk_fma_f32 v[130:131], v[154:155], v[114:115], v[74:75]
	v_pk_fma_f32 v[128:129], v[152:153], v[76:77], v[128:129]
	v_pk_fma_f32 v[130:131], v[180:181], v[78:79], v[130:131]
	v_pk_fma_f32 v[128:129], v[132:133], v[116:117], v[128:129]
	v_pk_fma_f32 v[130:131], v[136:137], v[118:119], v[130:131]
	v_pk_mul_f32 v[132:133], v[128:129], s[20:21] op_sel_hi:[1,0]
	v_pk_mul_f32 v[136:137], v[130:131], s[20:21] op_sel_hi:[1,0]
	v_exp_f32_e32 v132, v132
	v_exp_f32_e32 v133, v133
	v_exp_f32_e32 v136, v136
	v_exp_f32_e32 v137, v137
	v_pk_mul_f32 v[128:129], v[138:139], v[128:129]
	v_pk_add_f32 v[132:133], v[132:133], 1.0 op_sel_hi:[1,0]
	v_pk_mul_f32 v[130:131], v[134:135], v[130:131]
	v_pk_add_f32 v[136:137], v[136:137], 1.0 op_sel_hi:[1,0]
	v_rcp_f32_e32 v132, v132
	v_rcp_f32_e32 v133, v133
	v_rcp_f32_e32 v136, v136
	v_rcp_f32_e32 v137, v137
	v_add_u32_e32 v200, 0xb0, v160
	v_pk_mul_f32 v[128:129], v[128:129], v[132:133]
	v_add_u32_e32 v132, s4, v179
	v_pk_mul_f32 v[130:131], v[130:131], v[136:137]
	v_mad_i64_i32 v[132:133], s[8:9], v132, s19, v[148:149]
	v_cvt_pk_bf16_f32 v128, v128, v129
	v_cvt_pk_bf16_f32 v129, v130, v131
	v_cvt_pk_bf16_f32 v130, v142, v143
	v_cvt_pk_bf16_f32 v131, v140, v141
	v_lshl_add_u64 v[132:133], v[132:133], 0, v[150:151]
	global_store_dwordx4 v[132:133], v[128:131], off
	v_mov_b32_e32 v201, v167
	s_nop 0
	v_lshl_add_u32 v128, v200, 3, s67
	ds_read_b64 v[128:129], v128
	s_waitcnt lgkmcnt(0)
	v_pk_mul_f32 v[144:145], v[128:129], s[96:97] op_sel_hi:[1,0]
	v_fma_f32 v128, -v144, v144, v145
	v_max_f32_e32 v128, 0, v128
	v_add_f32_e32 v128, 0x3727c5ac, v128
	v_rsq_f32_e32 v160, v128
	s_nop 0
	v_mul_f32_e64 v180, v160, -v144
	s_waitcnt lgkmcnt(0)
	v_pk_fma_f32 v[128:129], v[222:223], v[180:181], v[226:227] op_sel_hi:[1,0,1]
	v_pk_fma_f32 v[130:131], v[224:225], v[180:181], v[228:229] op_sel_hi:[1,0,1]
	v_pk_fma_f32 v[132:133], v[230:231], v[180:181], v[234:235] op_sel_hi:[1,0,1]
	v_pk_fma_f32 v[134:135], v[232:233], v[180:181], v[236:237] op_sel_hi:[1,0,1]
	v_pk_fma_f32 v[128:129], v[36:37], v[160:161], v[128:129] op_sel_hi:[1,0,1]
	v_pk_fma_f32 v[130:131], v[38:39], v[160:161], v[130:131] op_sel_hi:[1,0,1]
	s_waitcnt lgkmcnt(0)
	v_pk_fma_f32 v[152:153], v[238:239], v[180:181], v[244:245] op_sel_hi:[1,0,1]
	v_pk_fma_f32 v[144:145], v[240:241], v[180:181], v[246:247] op_sel_hi:[1,0,1]
	v_pk_fma_f32 v[136:137], v[88:89], v[180:181], v[92:93] op_sel_hi:[1,0,1]
	v_pk_fma_f32 v[188:189], v[6:7], v[160:161], v[144:145] op_sel_hi:[1,0,1]
	v_pk_fma_f32 v[144:145], v[0:1], v[160:161], v[136:137] op_sel_hi:[1,0,1]
	v_pk_fma_f32 v[136:137], v[90:91], v[180:181], v[94:95] op_sel_hi:[1,0,1]
	v_pk_fma_f32 v[180:181], v[4:5], v[160:161], v[152:153] op_sel_hi:[1,0,1]
	v_pk_fma_f32 v[146:147], v[2:3], v[160:161], v[136:137] op_sel_hi:[1,0,1]
	v_mov_b32_dpp v136, v128 row_ror:1 row_mask:0xf bank_mask:0xf
	v_mov_b32_dpp v137, v129 row_ror:1 row_mask:0xf bank_mask:0xf
	v_cndmask_b32_e64 v191, v137, v218, s[42:43]
	v_cndmask_b32_e64 v190, v136, v217, s[42:43]
	v_mov_b32_dpp v179, v128 row_ror:2 row_mask:0xf bank_mask:0xf
	v_mov_b32_dpp v198, v129 row_ror:2 row_mask:0xf bank_mask:0xf
	v_mov_b32_dpp v204, v130 row_ror:2 row_mask:0xf bank_mask:0xf
	v_mov_b32_dpp v205, v131 row_ror:2 row_mask:0xf bank_mask:0xf
	v_cndmask_b32_e32 v199, v219, v198, vcc
	v_cndmask_b32_e32 v198, v177, v179, vcc
	v_mov_b32_dpp v202, v130 row_ror:1 row_mask:0xf bank_mask:0xf
	v_mov_b32_dpp v203, v131 row_ror:1 row_mask:0xf bank_mask:0xf
	s_waitcnt lgkmcnt(0)
	v_pk_fma_f32 v[152:153], v[198:199], v[112:113], v[72:73]
	v_cndmask_b32_e32 v179, v178, v205, vcc
	v_cndmask_b32_e32 v178, v173, v204, vcc
	v_pk_fma_f32 v[152:153], v[190:191], v[76:77], v[152:153]
	v_cndmask_b32_e64 v177, v203, v176, s[42:43]
	v_cndmask_b32_e64 v176, v202, v171, s[42:43]
	v_pk_fma_f32 v[154:155], v[178:179], v[114:115], v[74:75]
	v_pk_fma_f32 v[140:141], v[128:129], v[116:117], v[152:153]
	v_pk_fma_f32 v[154:155], v[176:177], v[78:79], v[154:155]
	v_pk_mul_f32 v[152:153], v[140:141], s[20:21] op_sel_hi:[1,0]
	v_pk_fma_f32 v[142:143], v[130:131], v[118:119], v[154:155]
	v_exp_f32_e32 v152, v152
	v_exp_f32_e32 v153, v153
	v_pk_mul_f32 v[154:155], v[142:143], s[20:21] op_sel_hi:[1,0]
	v_pk_mul_f32 v[140:141], v[180:181], v[140:141]
	v_exp_f32_e32 v154, v154
	v_exp_f32_e32 v155, v155
	v_pk_add_f32 v[152:153], v[152:153], 1.0 op_sel_hi:[1,0]
	v_pk_fma_f32 v[132:133], v[32:33], v[160:161], v[132:133] op_sel_hi:[1,0,1]
	v_rcp_f32_e32 v152, v152
	v_rcp_f32_e32 v153, v153
	v_pk_add_f32 v[154:155], v[154:155], 1.0 op_sel_hi:[1,0]
	v_rcp_f32_e32 v154, v154
	v_rcp_f32_e32 v155, v155
	v_pk_mul_f32 v[152:153], v[140:141], v[152:153]
	v_pk_mul_f32 v[140:141], v[188:189], v[142:143]
	v_pk_mul_f32 v[154:155], v[140:141], v[154:155]
	v_mov_b32_dpp v207, v133 row_ror:1 row_mask:0xf bank_mask:0xf
	v_mov_b32_dpp v208, v132 row_ror:2 row_mask:0xf bank_mask:0xf
	v_mov_b32_dpp v209, v133 row_ror:2 row_mask:0xf bank_mask:0xf
	v_pk_fma_f32 v[134:135], v[34:35], v[160:161], v[134:135] op_sel_hi:[1,0,1]
	v_mov_b32_dpp v206, v132 row_ror:1 row_mask:0xf bank_mask:0xf
	v_cndmask_b32_e64 v181, v207, v165, s[42:43]
	v_cndmask_b32_e32 v165, v164, v209, vcc
	v_cndmask_b32_e32 v164, v163, v208, vcc
	v_mov_b32_dpp v212, v134 row_ror:2 row_mask:0xf bank_mask:0xf
	v_mov_b32_dpp v213, v135 row_ror:2 row_mask:0xf bank_mask:0xf
	v_cndmask_b32_e64 v180, v206, v162, s[42:43]
	s_waitcnt lgkmcnt(0)
	v_pk_fma_f32 v[136:137], v[164:165], v[124:125], v[80:81]
	v_mov_b32_dpp v210, v134 row_ror:1 row_mask:0xf bank_mask:0xf
	v_mov_b32_dpp v211, v135 row_ror:1 row_mask:0xf bank_mask:0xf
	v_pk_fma_f32 v[136:137], v[180:181], v[84:85], v[136:137]
	v_cndmask_b32_e32 v157, v157, v213, vcc
	v_cndmask_b32_e32 v156, v156, v212, vcc
	v_pk_fma_f32 v[136:137], v[132:133], v[120:121], v[136:137]
	v_cndmask_b32_e64 v159, v211, v159, s[42:43]
	v_cndmask_b32_e64 v158, v210, v158, s[42:43]
	v_pk_fma_f32 v[138:139], v[156:157], v[126:127], v[82:83]
	v_pk_mul_f32 v[140:141], v[136:137], s[20:21] op_sel_hi:[1,0]
	v_pk_fma_f32 v[138:139], v[158:159], v[86:87], v[138:139]
	v_exp_f32_e32 v140, v140
	v_exp_f32_e32 v141, v141
	v_pk_fma_f32 v[138:139], v[134:135], v[122:123], v[138:139]
	v_pk_mul_f32 v[136:137], v[144:145], v[136:137]
	v_pk_mul_f32 v[142:143], v[138:139], s[20:21] op_sel_hi:[1,0]
	v_pk_add_f32 v[140:141], v[140:141], 1.0 op_sel_hi:[1,0]
	v_exp_f32_e32 v142, v142
	v_exp_f32_e32 v143, v143
	v_rcp_f32_e32 v140, v140
	v_rcp_f32_e32 v141, v141
	s_mov_b64 s[8:9], 0
	v_pk_add_f32 v[142:143], v[142:143], 1.0 op_sel_hi:[1,0]
	v_pk_mul_f32 v[140:141], v[136:137], v[140:141]
	v_rcp_f32_e32 v142, v142
	v_rcp_f32_e32 v143, v143
	v_pk_mul_f32 v[136:137], v[146:147], v[138:139]
	v_cvt_pk_bf16_f32 v138, v140, v141
	v_add_u32_e32 v140, s4, v200
	v_pk_mul_f32 v[142:143], v[136:137], v[142:143]
	v_mad_i64_i32 v[140:141], s[4:5], v140, s19, v[148:149]
	v_cvt_pk_bf16_f32 v136, v152, v153
	v_cvt_pk_bf16_f32 v137, v154, v155
	v_cvt_pk_bf16_f32 v139, v142, v143
	v_lshl_add_u64 v[140:141], v[140:141], 0, v[150:151]
	s_mov_b64 s[4:5], 0
	global_store_dwordx4 v[140:141], v[136:139], off
	s_and_saveexec_b64 s[22:23], s[24:25]
	s_cbranch_execz .LBB0_1401
	v_readlane_b32 s8, v255, 10
	s_mov_b32 s42, s57
	v_add_u32_e32 v160, -14, v169
	s_ashr_i32 s57, s56, 31
	v_readlane_b32 s9, v255, 11
	v_lshl_add_u64 v[136:137], s[56:57], 1, v[160:161]
	s_movk_i32 s19, 0x2c00
	v_mov_b64_e32 v[138:139], s[8:9]
	v_mad_u64_u32 v[138:139], s[8:9], v136, s19, v[138:139]
	v_mad_i32_i24 v139, v137, s19, v139
	v_lshl_add_u64 v[136:137], v[174:175], 2, v[138:139]
	s_cmp_eq_u32 s18, 7
	s_mov_b64 s[24:25], 0
	global_store_dwordx4 v[136:137], v[128:131], off
	global_store_dwordx4 v[136:137], v[132:135], off offset:16
	s_cbranch_scc0 .LBB0_1400
	s_ashr_i32 s8, s56, 3
	s_ashr_i32 s9, s8, 31
	s_mov_b64 s[24:25], -1
